# skinny_out staging: the 12 partial-row loads of an iteration issued up front (own registers per item) instead of 4 serialized load-wait-sum steps
# baseline (speedup 1.0000x reference)
; #define LAS __attribute__((address_space(3)))
; __device__ __forceinline__ u32x4 pack8(const f32x4& a, const f32x4& b) { u32x4 w; w.x = pk2(a[0], a[1]); w.y = pk2(a[2], a[3]); w.z = pk2(b[0], b[1]); w.w = pk2(b[2], b[3]); return w; }
; __device__ __forceinline__ void skinny_out(Frame& F, int l) {
;     ...
;         if (!staged) {
; #pragma unroll 4
;             for (int i = F.tid; i < 32 * (DM / 8); i += NT) { const int r = i / (DM / 8), c = i % (DM / 8);
;                 float p0[8], p1[8], p2[8];
;                 unpack8(*(const u32x4*)(brp + (size_t)r * DM + 8 * c), p0); unpack8(*(const u32x4*)(brp + (size_t)(32 + r) * DM + 8 * c), p1); unpack8(*(const u32x4*)(brp + (size_t)(64 + r) * DM + 8 * c), p2);
;                 f32x4 s0, s1;
; #pragma unroll
;                 for (int j = 0; j < 4; ++j) { s0[j] = p0[j] + p1[j] + p2[j]; s1[j] = p0[4 + j] + p1[4 + j] + p2[4 + j]; }
;                 *(LAS u32x4*)(F.lds + r * (DM * 2 + 16) + c * 16) = pack8(s0, s1); }
;             __syncthreads(); staged = true; }
.LBB0_1420:
	v_ashrrev_i32_e32 v150, 31, v2
	v_add_u32_sdwa v150, v2, v150 dst_sel:DWORD dst_unused:UNUSED_PAD src0_sel:DWORD src1_sel:BYTE_3
	v_ashrrev_i32_e32 v46, 8, v150
	v_mul_i32_i24_e32 v150, 0x100, v46
	v_ashrrev_i32_e32 v47, 31, v46
	v_lshlrev_b32_e32 v102, 3, v150
	v_lshlrev_b64 v[100:101], 12, v[46:47]
	v_sub_u32_e32 v102, v3, v102
	v_lshl_add_u64 v[100:101], s[18:19], 0, v[100:101]
	v_ashrrev_i32_e32 v103, 31, v102
	v_lshl_add_u64 v[108:109], v[102:103], 1, v[100:101]
	v_add_co_u32_e32 v104, vcc, s2, v108
	global_load_dwordx4 v[100:103], v[108:109], off
	s_nop 0
	v_addc_co_u32_e32 v105, vcc, 0, v109, vcc
	global_load_dwordx4 v[104:107], v[104:105], off
	v_add_co_u32_e32 v108, vcc, s38, v108
	v_mul_i32_i24_e32 v37, 0x1010, v46
	s_nop 0
	v_addc_co_u32_e32 v109, vcc, 0, v109, vcc
	global_load_dwordx4 v[108:111], v[108:109], off
	v_lshlrev_b32_e32 v150, 4, v150
	v_sub_u32_e32 v150, v37, v150
	v_add_u32_e32 v150, v4, v150
	s_movk_i32 s14, 0x17ff
	v_add_u32_e32 v3, 0x4000, v3
	v_add_u32_e32 v4, 0x8000, v4
	v_add_u32_e32 v151, 0x200, v2
	v_ashrrev_i32_e32 v112, 31, v151
	v_add_u32_sdwa v112, v151, v112 dst_sel:DWORD dst_unused:UNUSED_PAD src0_sel:DWORD src1_sel:BYTE_3
	v_ashrrev_i32_e32 v46, 8, v112
	v_mul_i32_i24_e32 v112, 0x100, v46
	v_sub_u32_e32 v151, v151, v112
	v_ashrrev_i32_e32 v47, 31, v46
	v_lshlrev_b64 v[112:113], 12, v[46:47]
	v_lshlrev_b32_e32 v114, 3, v151
	v_lshl_add_u64 v[112:113], s[18:19], 0, v[112:113]
	v_ashrrev_i32_e32 v115, 31, v114
	v_lshl_add_u64 v[120:121], v[114:115], 1, v[112:113]
	v_add_co_u32_e32 v116, vcc, s2, v120
	global_load_dwordx4 v[112:115], v[120:121], off
	s_nop 0
	v_addc_co_u32_e32 v117, vcc, 0, v121, vcc
	global_load_dwordx4 v[116:119], v[116:117], off
	v_add_co_u32_e32 v120, vcc, s38, v120
	v_mul_i32_i24_e32 v37, 0x1010, v46
	s_nop 0
	v_addc_co_u32_e32 v121, vcc, 0, v121, vcc
	global_load_dwordx4 v[120:123], v[120:121], off
	v_lshlrev_b32_e32 v151, 4, v151
	v_add3_u32 v151, 0, v37, v151
	v_add_u32_e32 v152, 0x400, v2
	v_ashrrev_i32_e32 v124, 31, v152
	v_add_u32_sdwa v124, v152, v124 dst_sel:DWORD dst_unused:UNUSED_PAD src0_sel:DWORD src1_sel:BYTE_3
	v_ashrrev_i32_e32 v46, 8, v124
	v_mul_i32_i24_e32 v124, 0x100, v46
	v_sub_u32_e32 v152, v152, v124
	v_ashrrev_i32_e32 v47, 31, v46
	v_lshlrev_b64 v[124:125], 12, v[46:47]
	v_lshlrev_b32_e32 v126, 3, v152
	v_lshl_add_u64 v[124:125], s[18:19], 0, v[124:125]
	v_ashrrev_i32_e32 v127, 31, v126
	v_lshl_add_u64 v[132:133], v[126:127], 1, v[124:125]
	v_add_co_u32_e32 v128, vcc, s2, v132
	global_load_dwordx4 v[124:127], v[132:133], off
	s_nop 0
	v_addc_co_u32_e32 v129, vcc, 0, v133, vcc
	global_load_dwordx4 v[128:131], v[128:129], off
	v_add_co_u32_e32 v132, vcc, s38, v132
	v_mul_i32_i24_e32 v37, 0x1010, v46
	s_nop 0
	v_addc_co_u32_e32 v133, vcc, 0, v133, vcc
	global_load_dwordx4 v[132:135], v[132:133], off
	v_lshlrev_b32_e32 v152, 4, v152
	v_add3_u32 v152, 0, v37, v152
	v_add_u32_e32 v153, 0x600, v2
	v_ashrrev_i32_e32 v136, 31, v153
	v_add_u32_sdwa v136, v153, v136 dst_sel:DWORD dst_unused:UNUSED_PAD src0_sel:DWORD src1_sel:BYTE_3
	v_ashrrev_i32_e32 v46, 8, v136
	v_mul_i32_i24_e32 v136, 0x100, v46
	v_sub_u32_e32 v153, v153, v136
	v_ashrrev_i32_e32 v47, 31, v46
	v_lshlrev_b64 v[136:137], 12, v[46:47]
	v_lshlrev_b32_e32 v138, 3, v153
	v_lshl_add_u64 v[136:137], s[18:19], 0, v[136:137]
	v_ashrrev_i32_e32 v139, 31, v138
	v_lshl_add_u64 v[144:145], v[138:139], 1, v[136:137]
	v_add_co_u32_e32 v140, vcc, s2, v144
	global_load_dwordx4 v[136:139], v[144:145], off
	s_nop 0
	v_addc_co_u32_e32 v141, vcc, 0, v145, vcc
	global_load_dwordx4 v[140:143], v[140:141], off
	v_add_co_u32_e32 v144, vcc, s38, v144
	v_mul_i32_i24_e32 v37, 0x1010, v46
	s_nop 0
	v_addc_co_u32_e32 v145, vcc, 0, v145, vcc
	global_load_dwordx4 v[144:147], v[144:145], off
	v_lshlrev_b32_e32 v153, 4, v153
	v_cmp_lt_i32_e32 vcc, s14, v2
	v_add3_u32 v153, 0, v37, v153
	v_add_u32_e32 v2, 0x800, v2
	s_or_b64 s[48:49], vcc, s[48:49]
	s_waitcnt vmcnt(9)
	v_lshlrev_b32_e32 v48, 16, v100
	v_and_b32_e32 v49, 0xffff0000, v100
	v_lshlrev_b32_e32 v100, 16, v101
	v_lshlrev_b32_e32 v50, 16, v104
	v_and_b32_e32 v51, 0xffff0000, v104
	v_and_b32_e32 v101, 0xffff0000, v101
	v_lshlrev_b32_e32 v104, 16, v105
	v_and_b32_e32 v105, 0xffff0000, v105
	v_pk_add_f32 v[48:49], v[48:49], v[50:51]
	v_lshlrev_b32_e32 v52, 16, v108
	v_and_b32_e32 v53, 0xffff0000, v108
	v_lshlrev_b32_e32 v108, 16, v109
	v_and_b32_e32 v109, 0xffff0000, v109
	v_pk_add_f32 v[100:101], v[100:101], v[104:105]
	v_pk_add_f32 v[48:49], v[48:49], v[52:53]
	v_lshlrev_b32_e32 v50, 16, v102
	v_and_b32_e32 v51, 0xffff0000, v102
	v_lshlrev_b32_e32 v52, 16, v106
	v_and_b32_e32 v53, 0xffff0000, v106
	v_pk_add_f32 v[104:105], v[100:101], v[108:109]
	v_lshlrev_b32_e32 v100, 16, v103
	v_and_b32_e32 v101, 0xffff0000, v103
	v_lshlrev_b32_e32 v102, 16, v107
	v_and_b32_e32 v103, 0xffff0000, v107
	v_lshlrev_b32_e32 v54, 16, v110
	v_and_b32_e32 v55, 0xffff0000, v110
	v_pk_add_f32 v[50:51], v[50:51], v[52:53]
	v_lshlrev_b32_e32 v106, 16, v111
	v_and_b32_e32 v107, 0xffff0000, v111
	v_pk_add_f32 v[100:101], v[100:101], v[102:103]
	v_pk_add_f32 v[50:51], v[50:51], v[54:55]
	v_pk_add_f32 v[106:107], v[100:101], v[106:107]
	v_cvt_pk_bf16_f32 v100, v48, v49
	v_cvt_pk_bf16_f32 v101, v104, v105
	v_cvt_pk_bf16_f32 v102, v50, v51
	v_cvt_pk_bf16_f32 v103, v106, v107
	ds_write_b128 v150, v[100:103]
	s_waitcnt vmcnt(8)
; #define LAS __attribute__((address_space(3)))
; __device__ __forceinline__ u32x4 pack8(const f32x4& a, const f32x4& b) { u32x4 w; w.x = pk2(a[0], a[1]); w.y = pk2(a[2], a[3]); w.z = pk2(b[0], b[1]); w.w = pk2(b[2], b[3]); return w; }
; __device__ __forceinline__ void skinny_out(Frame& F, int l) {
;     ...
;         if (!staged) {
; #pragma unroll 4
;             for (int i = F.tid; i < 32 * (DM / 8); i += NT) { const int r = i / (DM / 8), c = i % (DM / 8);
;                 float p0[8], p1[8], p2[8];
;                 unpack8(*(const u32x4*)(brp + (size_t)r * DM + 8 * c), p0); unpack8(*(const u32x4*)(brp + (size_t)(32 + r) * DM + 8 * c), p1); unpack8(*(const u32x4*)(brp + (size_t)(64 + r) * DM + 8 * c), p2);
;                 f32x4 s0, s1;
; #pragma unroll
;                 for (int j = 0; j < 4; ++j) { s0[j] = p0[j] + p1[j] + p2[j]; s1[j] = p0[4 + j] + p1[4 + j] + p2[4 + j]; }
;                 *(LAS u32x4*)(F.lds + r * (DM * 2 + 16) + c * 16) = pack8(s0, s1); }
;             __syncthreads(); staged = true; }
	v_lshlrev_b32_e32 v48, 16, v112
	v_and_b32_e32 v49, 0xffff0000, v112
	v_lshlrev_b32_e32 v112, 16, v113
	s_waitcnt vmcnt(7)
	v_lshlrev_b32_e32 v50, 16, v116
	v_and_b32_e32 v51, 0xffff0000, v116
	v_and_b32_e32 v113, 0xffff0000, v113
	v_lshlrev_b32_e32 v116, 16, v117
	v_and_b32_e32 v117, 0xffff0000, v117
	v_pk_add_f32 v[48:49], v[48:49], v[50:51]
	s_waitcnt vmcnt(6)
	v_lshlrev_b32_e32 v52, 16, v120
	v_and_b32_e32 v53, 0xffff0000, v120
	v_lshlrev_b32_e32 v120, 16, v121
	v_and_b32_e32 v121, 0xffff0000, v121
	v_pk_add_f32 v[112:113], v[112:113], v[116:117]
	v_pk_add_f32 v[48:49], v[48:49], v[52:53]
	v_lshlrev_b32_e32 v50, 16, v114
	v_and_b32_e32 v51, 0xffff0000, v114
	v_lshlrev_b32_e32 v52, 16, v118
	v_and_b32_e32 v53, 0xffff0000, v118
	v_pk_add_f32 v[116:117], v[112:113], v[120:121]
	v_lshlrev_b32_e32 v112, 16, v115
	v_and_b32_e32 v113, 0xffff0000, v115
	v_lshlrev_b32_e32 v114, 16, v119
	v_and_b32_e32 v115, 0xffff0000, v119
	v_lshlrev_b32_e32 v54, 16, v122
	v_and_b32_e32 v55, 0xffff0000, v122
	v_pk_add_f32 v[50:51], v[50:51], v[52:53]
	v_lshlrev_b32_e32 v118, 16, v123
	v_and_b32_e32 v119, 0xffff0000, v123
	v_pk_add_f32 v[112:113], v[112:113], v[114:115]
	v_pk_add_f32 v[50:51], v[50:51], v[54:55]
	v_pk_add_f32 v[118:119], v[112:113], v[118:119]
	v_cvt_pk_bf16_f32 v112, v48, v49
	v_cvt_pk_bf16_f32 v113, v116, v117
	v_cvt_pk_bf16_f32 v114, v50, v51
	v_cvt_pk_bf16_f32 v115, v118, v119
	ds_write_b128 v151, v[112:115]
	s_waitcnt vmcnt(5)
	v_lshlrev_b32_e32 v48, 16, v124
	v_and_b32_e32 v49, 0xffff0000, v124
	v_lshlrev_b32_e32 v124, 16, v125
	s_waitcnt vmcnt(4)
	v_lshlrev_b32_e32 v50, 16, v128
	v_and_b32_e32 v51, 0xffff0000, v128
	v_and_b32_e32 v125, 0xffff0000, v125
	v_lshlrev_b32_e32 v128, 16, v129
	v_and_b32_e32 v129, 0xffff0000, v129
	v_pk_add_f32 v[48:49], v[48:49], v[50:51]
	s_waitcnt vmcnt(3)
	v_lshlrev_b32_e32 v52, 16, v132
	v_and_b32_e32 v53, 0xffff0000, v132
	v_lshlrev_b32_e32 v132, 16, v133
	v_and_b32_e32 v133, 0xffff0000, v133
	v_pk_add_f32 v[124:125], v[124:125], v[128:129]
	v_pk_add_f32 v[48:49], v[48:49], v[52:53]
	v_lshlrev_b32_e32 v50, 16, v126
	v_and_b32_e32 v51, 0xffff0000, v126
	v_lshlrev_b32_e32 v52, 16, v130
	v_and_b32_e32 v53, 0xffff0000, v130
	v_pk_add_f32 v[128:129], v[124:125], v[132:133]
	v_lshlrev_b32_e32 v124, 16, v127
	v_and_b32_e32 v125, 0xffff0000, v127
	v_lshlrev_b32_e32 v126, 16, v131
	v_and_b32_e32 v127, 0xffff0000, v131
	v_lshlrev_b32_e32 v54, 16, v134
	v_and_b32_e32 v55, 0xffff0000, v134
	v_pk_add_f32 v[50:51], v[50:51], v[52:53]
	v_lshlrev_b32_e32 v130, 16, v135
	v_and_b32_e32 v131, 0xffff0000, v135
	v_pk_add_f32 v[124:125], v[124:125], v[126:127]
	v_pk_add_f32 v[50:51], v[50:51], v[54:55]
	v_pk_add_f32 v[130:131], v[124:125], v[130:131]
	v_cvt_pk_bf16_f32 v124, v48, v49
	v_cvt_pk_bf16_f32 v125, v128, v129
	v_cvt_pk_bf16_f32 v126, v50, v51
	v_cvt_pk_bf16_f32 v127, v130, v131
	ds_write_b128 v152, v[124:127]
	s_waitcnt vmcnt(2)
	v_lshlrev_b32_e32 v48, 16, v136
	v_and_b32_e32 v49, 0xffff0000, v136
	v_lshlrev_b32_e32 v136, 16, v137
	s_waitcnt vmcnt(1)
	v_lshlrev_b32_e32 v50, 16, v140
	v_and_b32_e32 v51, 0xffff0000, v140
	v_and_b32_e32 v137, 0xffff0000, v137
	v_lshlrev_b32_e32 v140, 16, v141
	v_and_b32_e32 v141, 0xffff0000, v141
	v_pk_add_f32 v[48:49], v[48:49], v[50:51]
	s_waitcnt vmcnt(0)
	v_lshlrev_b32_e32 v52, 16, v144
	v_and_b32_e32 v53, 0xffff0000, v144
	v_lshlrev_b32_e32 v144, 16, v145
	v_and_b32_e32 v145, 0xffff0000, v145
	v_pk_add_f32 v[136:137], v[136:137], v[140:141]
	v_pk_add_f32 v[48:49], v[48:49], v[52:53]
	v_lshlrev_b32_e32 v50, 16, v138
	v_and_b32_e32 v51, 0xffff0000, v138
	v_lshlrev_b32_e32 v52, 16, v142
	v_and_b32_e32 v53, 0xffff0000, v142
	v_pk_add_f32 v[140:141], v[136:137], v[144:145]
	v_lshlrev_b32_e32 v136, 16, v139
	v_and_b32_e32 v137, 0xffff0000, v139
	v_lshlrev_b32_e32 v138, 16, v143
	v_and_b32_e32 v139, 0xffff0000, v143
	v_lshlrev_b32_e32 v54, 16, v146
	v_and_b32_e32 v55, 0xffff0000, v146
	v_pk_add_f32 v[50:51], v[50:51], v[52:53]
	v_lshlrev_b32_e32 v142, 16, v147
	v_and_b32_e32 v143, 0xffff0000, v147
	v_pk_add_f32 v[136:137], v[136:137], v[138:139]
	v_pk_add_f32 v[50:51], v[50:51], v[54:55]
	v_pk_add_f32 v[142:143], v[136:137], v[142:143]
	v_cvt_pk_bf16_f32 v136, v48, v49
	v_cvt_pk_bf16_f32 v137, v140, v141
	v_cvt_pk_bf16_f32 v138, v50, v51
	v_cvt_pk_bf16_f32 v139, v142, v143
	ds_write_b128 v153, v[136:139]
	s_andn2_b64 exec, exec, s[48:49]
	s_cbranch_execnz .LBB0_1420
